# grid barrier: acquire-side L1 invalidate issued right after the arrival atomic so its latency overlaps the wait
# speedup vs baseline: 1.0264x; 1.0131x over previous
.LBB0_113:
	s_or_b64 exec, exec, s[16:17]
	buffer_inv sc1
	v_cvt_f32_u32_e32 v5, v3
	s_waitcnt vmcnt(1)
	v_readfirstlane_b32 s2, v4
	v_sub_u32_e32 v4, 0, v3
	v_rcp_iflag_f32_e32 v5, v5
	v_add_u32_e32 v6, s2, v2
	v_mul_f32_e32 v5, 0x4f7ffffe, v5
	v_cvt_u32_f32_e32 v5, v5
	v_mul_lo_u32 v2, v4, v5
	v_mul_hi_u32 v2, v5, v2
	v_add_u32_e32 v2, v5, v2
	v_mul_hi_u32 v2, v6, v2
	v_mul_lo_u32 v4, v2, v3
	v_sub_u32_e32 v4, v6, v4
	v_add_u32_e32 v5, 1, v2
	v_cmp_ge_u32_e32 vcc, v4, v3
	s_nop 1
	v_cndmask_b32_e32 v2, v2, v5, vcc
	v_sub_u32_e32 v5, v4, v3
	v_cndmask_b32_e32 v4, v4, v5, vcc
	v_add_u32_e32 v5, 1, v2
	v_cmp_ge_u32_e32 vcc, v4, v3
	v_add_u32_e32 v4, 1, v6
	s_nop 0
	v_cndmask_b32_e32 v2, v2, v5, vcc
	v_mul_lo_u32 v5, v3, v2
	v_add_u32_e32 v3, v5, v3
	v_cmp_ne_u32_e32 vcc, v4, v3
	s_and_saveexec_b64 s[2:3], vcc
	s_xor_b64 s[10:11], exec, s[2:3]
	s_cbranch_execz .LBB0_127
	s_waitcnt lgkmcnt(0)
	v_mov_b32_e32 v1, 0x3500
	global_load_dword v1, v1, s[60:61] sc1
	s_add_u32 s20, s60, 0x3500
	s_addc_u32 s21, s61, 0
	s_waitcnt vmcnt(0)
	v_cmp_eq_u32_e32 vcc, v1, v2
	s_and_saveexec_b64 s[16:17], vcc
	s_cbranch_execz .LBB0_126
	s_add_u32 s18, s88, 0xc67d200
	s_addc_u32 s19, s89, 0
	s_mov_b32 s2, 1
	s_mov_b64 s[22:23], 0
	v_mov_b32_e32 v1, 0
	s_branch .LBB0_117

.LBB0_126:
	s_or_b64 exec, exec, s[16:17]
	s_waitcnt vmcnt(0)
	s_waitcnt vmcnt(0)

.LBB0_144:
	s_or_b64 exec, exec, s[10:11]
	s_mov_b64 s[10:11], exec
	v_mbcnt_lo_u32_b32 v1, s10, 0
	v_mbcnt_hi_u32_b32 v1, s11, v1
	v_cmp_eq_u32_e32 vcc, 0, v1
	s_waitcnt vmcnt(0)
	s_and_saveexec_b64 s[16:17], vcc
	s_cbranch_execz .LBB0_146
	s_bcnt1_i32_b64 s2, s[10:11]
	v_mov_b32_e32 v1, 0x2000
	v_mov_b32_e32 v2, s2

.LBB0_330:
	s_or_b64 exec, exec, s[10:11]
	buffer_inv sc1
	v_cvt_f32_u32_e32 v5, v3
	s_waitcnt vmcnt(1)
	v_readfirstlane_b32 s2, v4
	v_sub_u32_e32 v4, 0, v3
	v_rcp_iflag_f32_e32 v5, v5
	v_add_u32_e32 v6, s2, v2
	v_mul_f32_e32 v5, 0x4f7ffffe, v5
	v_cvt_u32_f32_e32 v5, v5
	v_mul_lo_u32 v2, v4, v5
	v_mul_hi_u32 v2, v5, v2
	v_add_u32_e32 v2, v5, v2
	v_mul_hi_u32 v2, v6, v2
	v_mul_lo_u32 v4, v2, v3
	v_sub_u32_e32 v4, v6, v4
	v_add_u32_e32 v5, 1, v2
	v_cmp_ge_u32_e32 vcc, v4, v3
	s_nop 1
	v_cndmask_b32_e32 v2, v2, v5, vcc
	v_sub_u32_e32 v5, v4, v3
	v_cndmask_b32_e32 v4, v4, v5, vcc
	v_add_u32_e32 v5, 1, v2
	v_cmp_ge_u32_e32 vcc, v4, v3
	v_add_u32_e32 v4, 1, v6
	s_nop 0
	v_cndmask_b32_e32 v2, v2, v5, vcc
	v_mul_lo_u32 v5, v3, v2
	v_add_u32_e32 v3, v5, v3
	v_cmp_ne_u32_e32 vcc, v4, v3
	s_and_saveexec_b64 s[2:3], vcc
	s_xor_b64 s[8:9], exec, s[2:3]
	s_cbranch_execz .LBB0_344
	s_waitcnt lgkmcnt(0)
	v_mov_b32_e32 v1, 0x3500
	global_load_dword v1, v1, s[60:61] sc1
	s_add_u32 s14, s60, 0x3500
	s_addc_u32 s15, s61, 0
	s_waitcnt vmcnt(0)
	v_cmp_eq_u32_e32 vcc, v1, v2
	s_and_saveexec_b64 s[10:11], vcc
	s_cbranch_execz .LBB0_343
	s_add_u32 s12, s88, 0xc67d200
	s_addc_u32 s13, s89, 0
	s_mov_b32 s2, 1
	s_mov_b64 s[16:17], 0
	v_mov_b32_e32 v1, 0
	s_branch .LBB0_334

.LBB0_343:
	s_or_b64 exec, exec, s[10:11]
	s_waitcnt vmcnt(0)
	s_waitcnt vmcnt(0)

.LBB0_361:
	s_or_b64 exec, exec, s[8:9]
	s_mov_b64 s[8:9], exec
	v_mbcnt_lo_u32_b32 v1, s8, 0
	v_mbcnt_hi_u32_b32 v1, s9, v1
	v_cmp_eq_u32_e32 vcc, 0, v1
	s_waitcnt vmcnt(0)
	s_and_saveexec_b64 s[10:11], vcc
	s_cbranch_execz .LBB0_363
	s_bcnt1_i32_b64 s2, s[8:9]
	v_mov_b32_e32 v1, 0x2000
	v_mov_b32_e32 v2, s2

.LBB0_600:
	s_or_b64 exec, exec, s[10:11]
	buffer_inv sc1
	v_cvt_f32_u32_e32 v6, v4
	s_waitcnt vmcnt(1)
	v_readfirstlane_b32 s2, v5
	v_sub_u32_e32 v5, 0, v4
	v_rcp_iflag_f32_e32 v6, v6
	v_add_u32_e32 v7, s2, v3
	v_mul_f32_e32 v6, 0x4f7ffffe, v6
	v_cvt_u32_f32_e32 v6, v6
	v_mul_lo_u32 v3, v5, v6
	v_mul_hi_u32 v3, v6, v3
	v_add_u32_e32 v3, v6, v3
	v_mul_hi_u32 v3, v7, v3
	v_mul_lo_u32 v5, v3, v4
	v_sub_u32_e32 v5, v7, v5
	v_add_u32_e32 v6, 1, v3
	v_cmp_ge_u32_e32 vcc, v5, v4
	s_nop 1
	v_cndmask_b32_e32 v3, v3, v6, vcc
	v_sub_u32_e32 v6, v5, v4
	v_cndmask_b32_e32 v5, v5, v6, vcc
	v_add_u32_e32 v6, 1, v3
	v_cmp_ge_u32_e32 vcc, v5, v4
	v_add_u32_e32 v5, 1, v7
	s_nop 0
	v_cndmask_b32_e32 v3, v3, v6, vcc
	v_mul_lo_u32 v6, v4, v3
	v_add_u32_e32 v4, v6, v4
	v_cmp_ne_u32_e32 vcc, v5, v4
	s_and_saveexec_b64 s[2:3], vcc
	s_xor_b64 s[8:9], exec, s[2:3]
	s_cbranch_execz .LBB0_614
	s_waitcnt lgkmcnt(0)
	v_mov_b32_e32 v2, 0x3500
	global_load_dword v2, v2, s[60:61] sc1
	s_add_u32 s14, s60, 0x3500
	s_addc_u32 s15, s61, 0
	s_waitcnt vmcnt(0)
	v_cmp_eq_u32_e32 vcc, v2, v3
	s_and_saveexec_b64 s[10:11], vcc
	s_cbranch_execz .LBB0_613
	s_add_u32 s12, s88, 0xc67d200
	s_addc_u32 s13, s89, 0
	s_mov_b32 s2, 1
	s_mov_b64 s[16:17], 0
	v_mov_b32_e32 v2, 0
	s_branch .LBB0_604

.LBB0_631:
	s_or_b64 exec, exec, s[8:9]
	s_mov_b64 s[8:9], exec
	v_mbcnt_lo_u32_b32 v2, s8, 0
	v_mbcnt_hi_u32_b32 v2, s9, v2
	v_cmp_eq_u32_e32 vcc, 0, v2
	s_waitcnt vmcnt(0)
	s_and_saveexec_b64 s[10:11], vcc
	s_cbranch_execz .LBB0_633
	s_bcnt1_i32_b64 s2, s[8:9]
	v_mov_b32_e32 v2, 0x2000
	v_mov_b32_e32 v3, s2

.LBB0_660:
	s_or_b64 exec, exec, s[8:9]
	buffer_inv sc1
	v_cvt_f32_u32_e32 v6, v4
	s_waitcnt vmcnt(1)
	v_readfirstlane_b32 s2, v5
	v_sub_u32_e32 v5, 0, v4
	v_rcp_iflag_f32_e32 v6, v6
	v_add_u32_e32 v7, s2, v3
	v_mul_f32_e32 v6, 0x4f7ffffe, v6
	v_cvt_u32_f32_e32 v6, v6
	v_mul_lo_u32 v3, v5, v6
	v_mul_hi_u32 v3, v6, v3
	v_add_u32_e32 v3, v6, v3
	v_mul_hi_u32 v3, v7, v3
	v_mul_lo_u32 v5, v3, v4
	v_sub_u32_e32 v5, v7, v5
	v_add_u32_e32 v6, 1, v3
	v_cmp_ge_u32_e32 vcc, v5, v4
	s_nop 1
	v_cndmask_b32_e32 v3, v3, v6, vcc
	v_sub_u32_e32 v6, v5, v4
	v_cndmask_b32_e32 v5, v5, v6, vcc
	v_add_u32_e32 v6, 1, v3
	v_cmp_ge_u32_e32 vcc, v5, v4
	v_add_u32_e32 v5, 1, v7
	s_nop 0
	v_cndmask_b32_e32 v3, v3, v6, vcc
	v_mul_lo_u32 v6, v4, v3
	v_add_u32_e32 v4, v6, v4
	v_cmp_ne_u32_e32 vcc, v5, v4
	s_and_saveexec_b64 s[2:3], vcc
	s_xor_b64 s[6:7], exec, s[2:3]
	s_cbranch_execz .LBB0_674
	s_waitcnt lgkmcnt(0)
	v_mov_b32_e32 v2, 0x3500
	global_load_dword v2, v2, s[60:61] sc1
	s_add_u32 s12, s60, 0x3500
	s_addc_u32 s13, s61, 0
	s_waitcnt vmcnt(0)
	v_cmp_eq_u32_e32 vcc, v2, v3
	s_and_saveexec_b64 s[8:9], vcc
	s_cbranch_execz .LBB0_673
	s_add_u32 s10, s88, 0xc67d200
	s_addc_u32 s11, s89, 0
	s_mov_b32 s2, 1
	s_mov_b64 s[14:15], 0
	v_mov_b32_e32 v2, 0
	s_branch .LBB0_664

.LBB0_673:
	s_or_b64 exec, exec, s[8:9]
	s_waitcnt vmcnt(0)
	s_waitcnt vmcnt(0)

.LBB0_691:
	s_or_b64 exec, exec, s[6:7]
	s_mov_b64 s[6:7], exec
	v_mbcnt_lo_u32_b32 v2, s6, 0
	v_mbcnt_hi_u32_b32 v2, s7, v2
	v_cmp_eq_u32_e32 vcc, 0, v2
	s_waitcnt vmcnt(0)
	s_and_saveexec_b64 s[8:9], vcc
	s_cbranch_execz .LBB0_693
	s_bcnt1_i32_b64 s2, s[6:7]
	v_mov_b32_e32 v2, 0x2000
	v_mov_b32_e32 v3, s2

.LBB0_742:
	s_or_b64 exec, exec, s[12:13]
	buffer_inv sc1
	v_cvt_f32_u32_e32 v6, v4
	s_waitcnt vmcnt(1)
	v_readfirstlane_b32 s2, v5
	v_sub_u32_e32 v5, 0, v4
	v_rcp_iflag_f32_e32 v6, v6
	v_add_u32_e32 v7, s2, v3
	v_mul_f32_e32 v6, 0x4f7ffffe, v6
	v_cvt_u32_f32_e32 v6, v6
	v_mul_lo_u32 v3, v5, v6
	v_mul_hi_u32 v3, v6, v3
	v_add_u32_e32 v3, v6, v3
	v_mul_hi_u32 v3, v7, v3
	v_mul_lo_u32 v5, v3, v4
	v_sub_u32_e32 v5, v7, v5
	v_add_u32_e32 v6, 1, v3
	v_cmp_ge_u32_e32 vcc, v5, v4
	s_nop 1
	v_cndmask_b32_e32 v3, v3, v6, vcc
	v_sub_u32_e32 v6, v5, v4
	v_cndmask_b32_e32 v5, v5, v6, vcc
	v_add_u32_e32 v6, 1, v3
	v_cmp_ge_u32_e32 vcc, v5, v4
	v_add_u32_e32 v5, 1, v7
	s_nop 0
	v_cndmask_b32_e32 v3, v3, v6, vcc
	v_mul_lo_u32 v6, v4, v3
	v_add_u32_e32 v4, v6, v4
	v_cmp_ne_u32_e32 vcc, v5, v4
	s_and_saveexec_b64 s[2:3], vcc
	s_xor_b64 s[10:11], exec, s[2:3]
	s_cbranch_execz .LBB0_756
	s_waitcnt lgkmcnt(0)
	v_mov_b32_e32 v2, 0x3500
	global_load_dword v2, v2, s[60:61] sc1
	s_add_u32 s16, s60, 0x3500
	s_addc_u32 s17, s61, 0
	s_waitcnt vmcnt(0)
	v_cmp_eq_u32_e32 vcc, v2, v3
	s_and_saveexec_b64 s[12:13], vcc
	s_cbranch_execz .LBB0_755
	s_add_u32 s14, s88, 0xc67d200
	s_addc_u32 s15, s89, 0
	s_mov_b32 s2, 1
	s_mov_b64 s[18:19], 0
	v_mov_b32_e32 v2, 0
	s_branch .LBB0_746

.LBB0_755:
	s_or_b64 exec, exec, s[12:13]
	s_waitcnt vmcnt(0)
	s_waitcnt vmcnt(0)

.LBB0_773:
	s_or_b64 exec, exec, s[10:11]
	s_mov_b64 s[10:11], exec
	v_mbcnt_lo_u32_b32 v2, s10, 0
	v_mbcnt_hi_u32_b32 v2, s11, v2
	v_cmp_eq_u32_e32 vcc, 0, v2
	s_waitcnt vmcnt(0)
	s_and_saveexec_b64 s[12:13], vcc
	s_cbranch_execz .LBB0_775
	s_bcnt1_i32_b64 s2, s[10:11]
	v_mov_b32_e32 v2, 0x2000
	v_mov_b32_e32 v3, s2

.LBB0_1206:
	s_or_b64 exec, exec, s[10:11]
	buffer_inv sc1
	v_cvt_f32_u32_e32 v5, v3
	s_waitcnt vmcnt(1)
	v_readfirstlane_b32 s2, v4
	v_sub_u32_e32 v4, 0, v3
	v_rcp_iflag_f32_e32 v5, v5
	v_add_u32_e32 v6, s2, v2
	v_mul_f32_e32 v5, 0x4f7ffffe, v5
	v_cvt_u32_f32_e32 v5, v5
	v_mul_lo_u32 v2, v4, v5
	v_mul_hi_u32 v2, v5, v2
	v_add_u32_e32 v2, v5, v2
	v_mul_hi_u32 v2, v6, v2
	v_mul_lo_u32 v4, v2, v3
	v_sub_u32_e32 v4, v6, v4
	v_add_u32_e32 v5, 1, v2
	v_cmp_ge_u32_e32 vcc, v4, v3
	s_nop 1
	v_cndmask_b32_e32 v2, v2, v5, vcc
	v_sub_u32_e32 v5, v4, v3
	v_cndmask_b32_e32 v4, v4, v5, vcc
	v_add_u32_e32 v5, 1, v2
	v_cmp_ge_u32_e32 vcc, v4, v3
	v_add_u32_e32 v4, 1, v6
	s_nop 0
	v_cndmask_b32_e32 v2, v2, v5, vcc
	v_mul_lo_u32 v5, v3, v2
	v_add_u32_e32 v3, v5, v3
	v_cmp_ne_u32_e32 vcc, v4, v3
	s_and_saveexec_b64 s[2:3], vcc
	s_xor_b64 s[8:9], exec, s[2:3]
	s_cbranch_execz .LBB0_1220
	s_waitcnt lgkmcnt(0)
	v_mov_b32_e32 v1, 0x2000
	global_load_dword v1, v1, s[6:7] offset:1024 sc1
	s_add_u32 s14, s6, 0x2400
	s_addc_u32 s15, s7, 0
	s_waitcnt vmcnt(0)
	v_cmp_eq_u32_e32 vcc, v1, v2
	s_and_saveexec_b64 s[10:11], vcc
	s_cbranch_execz .LBB0_1219
	s_add_u32 s12, s88, 0xc67d200
	s_addc_u32 s13, s89, 0
	s_mov_b32 s2, 1
	s_mov_b64 s[16:17], 0
	v_mov_b32_e32 v1, 0
	s_branch .LBB0_1210

.LBB0_1237:
	s_or_b64 exec, exec, s[8:9]
	s_mov_b64 s[8:9], exec
	v_mbcnt_lo_u32_b32 v1, s8, 0
	v_mbcnt_hi_u32_b32 v1, s9, v1
	v_cmp_eq_u32_e32 vcc, 0, v1
	s_waitcnt vmcnt(0)
	s_and_saveexec_b64 s[10:11], vcc
	s_cbranch_execz .LBB0_1239
	s_bcnt1_i32_b64 s2, s[8:9]
	v_mov_b32_e32 v1, 0x2000
	v_mov_b32_e32 v2, s2
	global_atomic_add v1, v2, s[6:7] offset:1024
